# DMA issue: same-base pieces use a 64-bit scalar base in vcc instead of per-piece VALU offset adds
# baseline (speedup 1.0000x reference)
.Lfh:
	s_setprio 1
	s_waitcnt lgkmcnt(8)
	v_mfma_f32_32x32x16_bf16 v[64:79], v[168:171], v[80:83], v[238:253]
	ds_read_b128 v[180:183], v237 offset:53248
	ds_read_b128 v[176:179], v237 offset:53280
	v_add_u32_e32 v172, vcc_lo, v229
	v_add_u32_e32 v218, vcc_lo, v233
	v_mfma_f32_32x32x16_bf16 v[64:79], v[160:163], v[84:87], v[64:79]
	ds_read_b128 v[196:199], v237 offset:57856
	ds_read_b128 v[188:191], v237 offset:62464
	v_mfma_f32_32x32x16_bf16 v[64:79], v[164:167], v[88:91], v[64:79]
	ds_read_b128 v[200:203], v217 offset:13824
	ds_read_b128 v[184:187], v217 offset:13856
	v_mfma_f32_32x32x16_bf16 v[64:79], v[152:155], v[92:95], v[64:79]
	ds_read_b128 v[204:207], v237 offset:57888
	ds_read_b128 v[192:195], v237 offset:62496
	s_waitcnt lgkmcnt(8)
	v_mfma_f32_32x32x16_bf16 v[64:79], v[156:159], v[96:99], v[64:79]
	ds_read_b128 v[168:171], v172 offset:8704
	ds_read_b128 v[160:163], v172 offset:8736
	v_mfma_f32_32x32x16_bf16 v[64:79], v[128:131], v[100:103], v[64:79]
	ds_read_b128 v[164:167], v172 offset:8768
	ds_read_b128 v[152:155], v172 offset:8800
	v_mfma_f32_32x32x16_bf16 v[64:79], v[132:135], v[104:107], v[64:79]
	ds_read_b128 v[156:159], v172 offset:8832
	ds_read_b128 v[128:131], v172 offset:8864
	v_mfma_f32_32x32x16_bf16 v[64:79], v[136:139], v[108:111], v[64:79]
	ds_read_b128 v[132:135], v172 offset:8896
	ds_read_b128 v[136:139], v172 offset:8928
	v_mfma_f32_32x32x16_bf16 v[64:79], v[140:143], v[112:115], v[64:79]
	ds_read_b128 v[140:143], v218 offset:22016
	ds_read_b128 v[172:175], v218 offset:22112
	v_mfma_f32_32x32x16_bf16 v[64:79], v[144:147], v[116:119], v[64:79]
	ds_read_b128 v[144:147], v218 offset:22048
	v_mfma_f32_32x32x16_bf16 v[64:79], v[148:151], v[120:123], v[64:79]
	ds_read_b128 v[148:151], v218 offset:22080
	v_mfma_f32_32x32x16_bf16 v[64:79], v[208:211], v[124:127], v[64:79]
	s_setprio 0
	s_barrier
	s_and_b64 vcc, exec, s[68:69]
	s_cbranch_vccnz .Ldmq_end
	s_cmp_ge_u32 s85, 4
	s_cbranch_scc1 .Lxdq_y
	s_add_u32 vcc_lo, s8, s94
	s_addc_u32 vcc_hi, s9, 0
	s_add_i32 m0, s99, 0x0
	s_nop 0
	global_load_lds_dwordx4 v221, vcc
	s_add_i32 m0, s99, 0x1000
	s_nop 0
	global_load_lds_dwordx4 v222, vcc
	s_add_i32 m0, s99, 0x2000
	s_nop 0
	global_load_lds_dwordx4 v223, vcc
	s_add_i32 m0, s99, 0x3000
	s_nop 0
	global_load_lds_dwordx4 v224, vcc
	s_add_i32 m0, s99, 0x4000
	v_add_u32_e32 v255, s92, v225
	global_load_lds_dwordx4 v255, s[46:47]
	s_add_i32 m0, s99, 0x5000
	v_add_u32_e32 v255, s90, v226
	global_load_lds_dwordx4 v255, s[52:53]
	s_branch .Ldmq_end
.Lxdq_y:
	s_lshl_b32 s92, s34, s96
	s_cmp_ge_u32 s45, 2
	s_cselect_b32 s93, s98, s99
	s_add_i32 m0, s93, 0x6000
	v_add_u32_e32 v255, s92, v221
	global_load_lds_dwordx4 v255, s[50:51]
	s_add_u32 vcc_lo, s54, s91
	s_addc_u32 vcc_hi, s55, 0
	s_add_i32 m0, s98, 0x7000
	s_nop 0
	global_load_lds_dwordx4 v222, vcc
	s_add_i32 m0, s98, 0x8000
	s_nop 0
	global_load_lds_dwordx4 v223, vcc
	s_add_i32 m0, s98, 0x9000
	s_nop 0
	global_load_lds_dwordx4 v224, vcc
	s_add_i32 m0, s98, 0xa000
	s_nop 0
	global_load_lds_dwordx4 v225, vcc
